# v3 + shorter grid barrier: XCD-last workgroup does wbl2 + TOP++ and every workgroup polls TOP directly (drops the TOPGEN and XGEN hops and the integer divisions)
# baseline (speedup 1.0000x reference)
; #define LAS __attribute__((address_space(3)))
; __device__ __forceinline__ int opaque_tid(int wv) { int l; asm volatile("v_mbcnt_lo_u32_b32 %0, -1, 0\n\tv_mbcnt_hi_u32_b32 %0, -1, %0" : "=v"(l)); return (wv << 6) | l; }
; __global__ void __launch_bounds__(NTHR, 2) fwd_kernel(Args a_unused) {
;     extern __shared__ __attribute__((aligned(16))) unsigned char lds_raw[];
;     LAS unsigned char* lds = (LAS unsigned char*)lds_raw;
;     cg::grid_group grid = cg::this_grid();
;     const int G = NWG, bid = blockIdx.x;
;     const int wv = __builtin_amdgcn_readfirstlane(threadIdx.x >> 6);
;     ArgsCP ap = (ArgsCP)__builtin_amdgcn_kernarg_segment_ptr();
;     ...
;     volatile LAS unsigned* xst = (volatile LAS unsigned*)(lds + LDS_BYTES - 16);
;     { const int t_ = opaque_tid(wv); if (t_ < 4) xst[t_] = 0u; }
;     if (load_args(ap).ws == nullptr) grid.sync();
;     (void)xcd_barrier_post((unsigned*)load_args(ap).ws, xst, opaque_tid(wv) == 0);
_Z10fwd_kernel4Args:
	s_mov_b64 s[46:47], s[0:1]
	v_writelane_b32 v255, 0, 62
	v_and_b32_e32 v1, 0x3ff, v0
	s_mov_b32 s60, s2
	s_add_u32 s2, s46, 0x90
	v_readfirstlane_b32 s0, v1
	s_addc_u32 s3, s47, 0
	v_mbcnt_lo_u32_b32 v2, -1, 0
	v_mbcnt_hi_u32_b32 v2, -1, v2
	s_nop 0
	v_writelane_b32 v252, s0, 0
	s_andn2_b32 s0, s0, 63
	v_or_b32_e32 v2, s0, v2
	v_writelane_b32 v252, s0, 1
	v_cmp_gt_i32_e32 vcc, 4, v2
	s_and_saveexec_b64 s[0:1], vcc
	v_lshl_add_u32 v2, v2, 2, 0
	v_add_u32_e32 v2, 0x23ff0, v2
	v_mov_b32_e32 v3, 0
	ds_write_b32 v2, v3
	s_or_b64 exec, exec, s[0:1]
	s_mov_b64 s[0:1], s[46:47]
	s_load_dwordx2 s[0:1], s[0:1], 0x88
	s_waitcnt lgkmcnt(0)
	s_cmp_lg_u64 s[0:1], 0
	s_cbranch_scc1 .LBB0_14
	v_lshrrev_b32_e32 v2, 20, v0
	v_lshrrev_b32_e32 v0, 10, v0
	v_or_b32_e32 v0, v0, v2
	s_movk_i32 s0, 0x3ff
	v_and_or_b32 v0, v0, s0, v1
	v_cmp_eq_u32_e32 vcc, 0, v0
	s_barrier
	s_and_saveexec_b64 s[0:1], vcc
	s_cbranch_execz .LBB0_13
	buffer_wbl2 sc1
	s_load_dwordx2 s[2:3], s[2:3], 0x58
	v_mov_b32_e32 v2, 0
	s_mov_b64 s[4:5], exec
	v_mbcnt_lo_u32_b32 v1, s4, 0
	v_mbcnt_hi_u32_b32 v1, s5, v1
	s_waitcnt lgkmcnt(0)
	global_load_dword v0, v2, s[2:3] offset:40
	v_cmp_eq_u32_e32 vcc, 0, v1
	s_and_saveexec_b64 s[6:7], vcc
	s_cbranch_execz .LBB0_6
	s_bcnt1_i32_b64 s4, s[4:5]
	v_mov_b32_e32 v3, s4
	global_atomic_add v3, v2, v3, s[2:3] offset:32 sc0

; __device__ __forceinline__ unsigned xb_ld(unsigned* p)              { return __hip_atomic_load(p, __ATOMIC_RELAXED, __HIP_MEMORY_SCOPE_AGENT); }
; __device__ __forceinline__ unsigned xb_add(unsigned* p, unsigned v) { return __hip_atomic_fetch_add(p, v, __ATOMIC_RELAXED, __HIP_MEMORY_SCOPE_AGENT); }
; #define XB_SPIN(cond, bar) do { unsigned _sp = 0; while (cond) { __builtin_amdgcn_s_sleep(1); \
;     if ((++_sp & 255u) == 0u) { if (xb_ld(&(bar)[XB_TMO])) break; if (_sp > XB_SPIN_CAP) { atomicAdd(&(bar)[XB_TMO], 1u); break; } } } } while (0)
; __device__ __forceinline__ void xcd_barrier(const XcdBarrier& b, bool t0) {
;     asm volatile("s_waitcnt vmcnt(0)" ::: "memory");
;     __syncthreads();
;     if (t0) {
;         unsigned* bar = b.bar;
;         __builtin_amdgcn_s_waitcnt(0);
;         unsigned nloc = b.st[0], nx = b.st[1];
;         if (nloc == 0u) { xcd_barrier_complete(bar, b.x, nloc, nx); b.st[0] = nloc; b.st[1] = nx; }
;         const unsigned old = xb_add(&bar[XB_XSUB(b.x)], 1u);
;         const unsigned gen = old / nloc;
;         if (old + 1u == (gen + 1u) * nloc) {
;             __builtin_amdgcn_fence(__ATOMIC_RELEASE, "agent");
;             asm volatile("s_waitcnt vmcnt(0)" ::: "memory");
;             const unsigned og = xb_add(&bar[XB_TOP], 1u);
;             const unsigned tg = og / nx;
;             if (og + 1u == (tg + 1u) * nx) xb_add(&bar[XB_TOPGEN], 1u);
;             else XB_SPIN(xb_ld(&bar[XB_TOPGEN]) == tg, bar);
;             __builtin_amdgcn_fence(__ATOMIC_ACQUIRE, "agent");
;             xb_add(&bar[XB_XGEN(b.x)], 1u);
;             asm volatile("s_waitcnt vmcnt(0)" ::: "memory");
;         } else {
;             XB_SPIN(xb_ld(&bar[XB_XGEN(b.x)]) == gen, bar);
;             __builtin_amdgcn_fence(__ATOMIC_ACQUIRE, "agent");
;             asm volatile("s_waitcnt vmcnt(0)" ::: "memory");
;         }
;     }
;     __syncthreads();
; }
.LBB0_133:
	s_lshl_b32 s4, s18, 8
	s_add_u32 s4, s2, s4
	s_addc_u32 s5, s3, 0
	v_mov_b32_e32 v3, 1
	v_mov_b32_e32 v4, 0x1000
	global_atomic_add v3, v4, v3, s[4:5] offset:1024 sc0
	v_readlane_b32 s9, v255, 62
	s_waitcnt lgkmcnt(0)
	v_readfirstlane_b32 s7, v2
	v_readfirstlane_b32 s8, v0
	s_add_u32 s9, s9, 1
	s_mul_i32 s7, s7, s9
	s_mul_i32 s8, s8, s9
	v_writelane_b32 v255, s9, 62
	s_waitcnt vmcnt(0)
	v_readfirstlane_b32 s6, v3
	s_add_u32 s6, s6, 1
	s_cmp_lg_u32 s6, s7
	s_cbranch_scc1 .Lgs0_poll
	buffer_wbl2 sc1
	s_waitcnt vmcnt(0)
	v_mov_b32_e32 v3, 1
	v_mov_b32_e32 v4, 0x3000
	global_atomic_add v4, v3, s[2:3] offset:1024
.Lgs0_poll:
	v_mov_b32_e32 v4, 0x3000
	s_mov_b32 s4, 0
.Lgs0_spin:
	global_load_dword v3, v4, s[2:3] offset:1024 sc1
	s_waitcnt vmcnt(0)
	v_readfirstlane_b32 s5, v3
	s_cmp_ge_u32 s5, s8
	s_cbranch_scc1 .Lgs0_done
	s_sleep 1
	s_add_u32 s4, s4, 1
	s_cmp_lt_u32 s4, 0x40000
	s_cbranch_scc1 .Lgs0_spin
.Lgs0_done:
	buffer_inv sc1
	s_waitcnt vmcnt(0)

; __device__ __forceinline__ unsigned xb_ld(unsigned* p)              { return __hip_atomic_load(p, __ATOMIC_RELAXED, __HIP_MEMORY_SCOPE_AGENT); }
; __device__ __forceinline__ unsigned xb_add(unsigned* p, unsigned v) { return __hip_atomic_fetch_add(p, v, __ATOMIC_RELAXED, __HIP_MEMORY_SCOPE_AGENT); }
; #define XB_SPIN(cond, bar) do { unsigned _sp = 0; while (cond) { __builtin_amdgcn_s_sleep(1); \
;     if ((++_sp & 255u) == 0u) { if (xb_ld(&(bar)[XB_TMO])) break; if (_sp > XB_SPIN_CAP) { atomicAdd(&(bar)[XB_TMO], 1u); break; } } } } while (0)
; __device__ __forceinline__ void xcd_barrier(const XcdBarrier& b, bool t0) {
;     asm volatile("s_waitcnt vmcnt(0)" ::: "memory");
;     __syncthreads();
;     if (t0) {
;         unsigned* bar = b.bar;
;         __builtin_amdgcn_s_waitcnt(0);
;         unsigned nloc = b.st[0], nx = b.st[1];
;         if (nloc == 0u) { xcd_barrier_complete(bar, b.x, nloc, nx); b.st[0] = nloc; b.st[1] = nx; }
;         const unsigned old = xb_add(&bar[XB_XSUB(b.x)], 1u);
;         const unsigned gen = old / nloc;
;         if (old + 1u == (gen + 1u) * nloc) {
;             __builtin_amdgcn_fence(__ATOMIC_RELEASE, "agent");
;             asm volatile("s_waitcnt vmcnt(0)" ::: "memory");
;             const unsigned og = xb_add(&bar[XB_TOP], 1u);
;             const unsigned tg = og / nx;
;             if (og + 1u == (tg + 1u) * nx) xb_add(&bar[XB_TOPGEN], 1u);
;             else XB_SPIN(xb_ld(&bar[XB_TOPGEN]) == tg, bar);
;             __builtin_amdgcn_fence(__ATOMIC_ACQUIRE, "agent");
;             xb_add(&bar[XB_XGEN(b.x)], 1u);
;             asm volatile("s_waitcnt vmcnt(0)" ::: "memory");
;         } else {
;             XB_SPIN(xb_ld(&bar[XB_XGEN(b.x)]) == gen, bar);
;             __builtin_amdgcn_fence(__ATOMIC_ACQUIRE, "agent");
;             asm volatile("s_waitcnt vmcnt(0)" ::: "memory");
;         }
;     }
;     __syncthreads();
; }
.LBB0_932:
	s_lshl_b32 s6, s20, 8
	s_add_u32 s6, s2, s6
	s_addc_u32 s7, s3, 0
	v_mov_b32_e32 v3, 1
	v_mov_b32_e32 v4, 0x1000
	global_atomic_add v3, v4, v3, s[6:7] offset:1024 sc0
	v_readlane_b32 s11, v255, 62
	s_waitcnt lgkmcnt(0)
	v_readfirstlane_b32 s9, v2
	v_readfirstlane_b32 s10, v0
	s_add_u32 s11, s11, 1
	s_mul_i32 s9, s9, s11
	s_mul_i32 s10, s10, s11
	v_writelane_b32 v255, s11, 62
	s_waitcnt vmcnt(0)
	v_readfirstlane_b32 s8, v3
	s_add_u32 s8, s8, 1
	s_cmp_lg_u32 s8, s9
	s_cbranch_scc1 .Lgs10_poll
	buffer_wbl2 sc1
	s_waitcnt vmcnt(0)
	v_mov_b32_e32 v3, 1
	v_mov_b32_e32 v4, 0x3000
	global_atomic_add v4, v3, s[2:3] offset:1024
.Lgs10_poll:
	v_mov_b32_e32 v4, 0x3000
	s_mov_b32 s6, 0
.Lgs10_spin:
	global_load_dword v3, v4, s[2:3] offset:1024 sc1
	s_waitcnt vmcnt(0)
	v_readfirstlane_b32 s7, v3
	s_cmp_ge_u32 s7, s10
	s_cbranch_scc1 .Lgs10_done
	s_sleep 1
	s_add_u32 s6, s6, 1
	s_cmp_lt_u32 s6, 0x40000
	s_cbranch_scc1 .Lgs10_spin

; __device__ __forceinline__ unsigned xb_ld(unsigned* p)              { return __hip_atomic_load(p, __ATOMIC_RELAXED, __HIP_MEMORY_SCOPE_AGENT); }
; #define XB_SPIN(cond, bar) do { unsigned _sp = 0; while (cond) { __builtin_amdgcn_s_sleep(1); \
;     if ((++_sp & 255u) == 0u) { if (xb_ld(&(bar)[XB_TMO])) break; if (_sp > XB_SPIN_CAP) { atomicAdd(&(bar)[XB_TMO], 1u); break; } } } } while (0)
; __device__ __forceinline__ void xcd_barrier(const XcdBarrier& b, bool t0) {
;     ...
;             XB_SPIN(xb_ld(&bar[XB_XGEN(b.x)]) == gen, bar);
;             __builtin_amdgcn_fence(__ATOMIC_ACQUIRE, "agent");
;             asm volatile("s_waitcnt vmcnt(0)" ::: "memory");
;         }
;     }
;     __syncthreads();
.Lgs12_done:
	buffer_inv sc1
	s_waitcnt vmcnt(0)
	s_mov_b64 s[6:7], 0
	s_getpc_b64 s[98:99]
